# attention group loop unrolled by two with current/next K-V register sets exchanged in the second copy: the 16 v_mov_b64 copies and the per-group vmcnt drain are gone
# speedup vs baseline: 1.0059x; 1.0059x over previous
.LBB0_634:
	v_add_f32_e32 v12, 0, v69
	v_add_f32_e32 v12, v70, v12
	v_add_f32_e32 v12, v71, v12
	v_add_f32_e32 v12, v72, v12
	v_add_f32_e32 v12, v73, v12
	v_add_f32_e32 v12, v74, v12
	v_add_f32_e32 v12, v75, v12
	v_add_f32_e32 v112, v76, v12
	ds_read_b64_tr_b16 v[114:115], v106 offset:16384
	ds_read_b64_tr_b16 v[116:117], v107 offset:16384
	ds_read_b64_tr_b16 v[118:119], v106 offset:16416
	ds_read_b64_tr_b16 v[120:121], v107 offset:16416
	ds_read_b64_tr_b16 v[122:123], v106 offset:16448
	ds_read_b64_tr_b16 v[124:125], v107 offset:16448
	ds_read_b64_tr_b16 v[126:127], v106 offset:16480
	ds_read_b64_tr_b16 v[128:129], v107 offset:16480
	v_fmac_f32_e32 v112, v111, v68
	s_setprio 1
	s_waitcnt lgkmcnt(6)
	v_mfma_f32_16x16x32_bf16 v[8:11], v[114:117], v[64:67], v[8:11]
	s_waitcnt lgkmcnt(4)
	v_mfma_f32_16x16x32_bf16 v[4:7], v[118:121], v[64:67], v[4:7]
	s_waitcnt lgkmcnt(2)
	v_mfma_f32_16x16x32_bf16 v[0:3], v[122:125], v[64:67], v[0:3]
	s_waitcnt lgkmcnt(0)
	v_mfma_f32_16x16x32_bf16 v[12:15], v[126:129], v[64:67], v[32:35]
	s_setprio 0
	s_add_i32 s16, s16, 1
	s_cmp_eq_u32 s16, 11
	s_cbranch_scc1 .LBB0_636
	v_mov_b32_e32 v111, v112
	s_mov_b32 s18, s17
	v_mov_b32_e32 v32, v12
	v_mov_b32_e32 v33, v13
	v_mov_b32_e32 v34, v14
	v_mov_b32_e32 v35, v15

.Latt2_629:
	s_lshl_b32 s20, -1, s13
	s_andn2_b32 s22, s10, s20
	s_lshr_b32 s20, s15, s13
	s_lshl_b32 s21, s21, 5
	s_add_i32 s20, s20, s21
	s_lshr_b32 s18, s14, s13
	s_sub_i32 s23, s20, 64
	v_add_u32_e32 v70, s23, v49
	s_add_i32 s18, s18, -1
	v_min_i32_e32 v68, s18, v70
	v_cmp_lt_i32_e32 vcc, -1, v70
	v_add_u32_e32 v92, s23, v103
	v_min_i32_e32 v84, s18, v92
	v_cndmask_b32_e32 v68, 0, v68, vcc
	v_lshlrev_b32_e32 v68, s13, v68
	v_add_u32_e32 v68, s22, v68
	v_mad_u64_u32 v[68:69], s[20:21], v68, s31, v[98:99]
	global_load_dwordx4 v[76:79], v68, s[6:7] offset:768
	global_load_dwordx4 v[72:75], v68, s[6:7] offset:832
	v_add_u32_e32 v68, 16, v70
	v_min_i32_e32 v69, s18, v68
	v_cmp_lt_i32_e32 vcc, -1, v68
	v_add_u32_e32 v85, 8, v92
	v_min_i32_e32 v85, s18, v85
	v_cndmask_b32_e32 v68, 0, v69, vcc
	v_cmp_lt_i32_e32 vcc, -1, v92
	v_add_u32_e32 v93, 16, v92
	v_min_i32_e32 v93, s18, v93
	v_cndmask_b32_e32 v84, 0, v84, vcc
	v_cmp_lt_i32_e32 vcc, -9, v92
	v_add_u32_e32 v94, 24, v92
	v_min_i32_e32 v94, s18, v94
	v_cndmask_b32_e32 v85, 0, v85, vcc
	v_cmp_lt_i32_e32 vcc, s55, v92
	v_lshlrev_b32_e32 v84, s13, v84
	v_lshlrev_b32_e32 v85, s13, v85
	v_cndmask_b32_e32 v93, 0, v93, vcc
	v_cmp_lt_i32_e32 vcc, s96, v92
	v_lshlrev_b32_e32 v93, s13, v93
	v_lshlrev_b32_e32 v68, s13, v68
	v_cndmask_b32_e32 v92, 0, v94, vcc
	v_lshlrev_b32_e32 v92, s13, v92
	v_add_u32_e32 v84, s22, v84
	v_add_u32_e32 v85, s22, v85
	v_add_u32_e32 v93, s22, v93
	v_add_u32_e32 v92, s22, v92
	v_add_u32_e32 v68, s22, v68
	v_mul_lo_u32 v84, v84, s31
	v_mul_lo_u32 v85, v85, s31
	v_mul_lo_u32 v93, v93, s31
	v_mul_lo_u32 v92, v92, s31
	v_mad_u64_u32 v[64:65], s[20:21], v68, s31, v[98:99]
	v_or_b32_e32 v84, v84, v104
	v_or_b32_e32 v80, v85, v104
	v_or_b32_e32 v93, v93, v104
	v_or_b32_e32 v88, v92, v104
	global_load_dwordx4 v[68:71], v64, s[6:7] offset:768
	s_nop 0
	global_load_dwordx4 v[64:67], v64, s[6:7] offset:832
	s_nop 0
	global_load_dwordx4 v[84:87], v84, s[6:7] offset:1536
	s_nop 0
	global_load_dwordx4 v[80:83], v80, s[6:7] offset:1536
	s_nop 0
	global_load_dwordx4 v[92:95], v93, s[6:7] offset:1536
	s_nop 0
	global_load_dwordx4 v[88:91], v88, s[6:7] offset:1536
	s_lshr_b32 s13, s15, s12
	v_lshrrev_b32_e32 v112, s12, v110
	s_lshl_b32 s18, s19, 5
	s_lshr_b32 s19, s14, s12
	s_lshr_b32 s12, s12, 1
	s_waitcnt vmcnt(11)
	ds_write_b128 v108, v[44:47] offset:16384
	s_waitcnt vmcnt(10)
	ds_write_b128 v108, v[52:55] offset:17536
	s_waitcnt vmcnt(9)
	ds_write_b128 v108, v[56:59] offset:18688
	s_waitcnt vmcnt(8)
	ds_write_b128 v108, v[60:63] offset:19840
	v_add_u32_e32 v52, s13, v105
	v_sub_u32_e32 v53, v52, v112
	s_mul_i32 s12, s12, 6
	v_add_u32_e32 v53, s18, v53
	s_add_i32 s12, s12, s1
	s_mulk_i32 s12, 0x210
	v_add_u32_e32 v55, 1, v53
	v_add_u32_e32 v45, 2, v53
	v_add_u32_e32 v47, 3, v53
	v_add_u32_e32 v61, 16, v53
	v_add_u32_e32 v63, 17, v53
	v_add_u32_e32 v57, 18, v53
	v_add_u32_e32 v59, 19, v53
	s_add_i32 s12, s12, 0
	v_med3_i32 v54, v53, s30, 64
	v_med3_i32 v44, v55, s30, 64
	v_med3_i32 v46, v45, s30, 64
	v_med3_i32 v60, v47, s30, 64
	v_med3_i32 v62, v61, s30, 64
	v_med3_i32 v56, v63, s30, 64
	v_med3_i32 v58, v57, s30, 64
	v_med3_i32 v113, v59, s30, 64
	v_lshl_add_u32 v54, v54, 2, s12
	v_lshl_add_u32 v44, v44, 2, s12
	v_lshl_add_u32 v46, v46, 2, s12
	v_lshl_add_u32 v60, v60, 2, s12
	v_lshl_add_u32 v62, v62, 2, s12
	v_lshl_add_u32 v56, v56, 2, s12
	v_lshl_add_u32 v58, v58, 2, s12
	v_lshl_add_u32 v113, v113, 2, s12
	ds_read_b32 v54, v54 offset:256
	ds_read_b32 v44, v44 offset:256
	ds_read_b32 v46, v46 offset:256
	ds_read_b32 v60, v60 offset:256
	ds_read_b32 v62, v62 offset:256
	ds_read_b32 v56, v56 offset:256
	ds_read_b32 v58, v58 offset:256
	ds_read_b32 v113, v113 offset:256
	s_waitcnt lgkmcnt(7)
	s_waitcnt lgkmcnt(6)
	s_waitcnt lgkmcnt(5)
	s_waitcnt lgkmcnt(4)
	s_waitcnt lgkmcnt(3)
	s_waitcnt lgkmcnt(2)
	s_waitcnt lgkmcnt(1)
	s_waitcnt lgkmcnt(0)
	s_setprio 1
	v_mfma_f32_16x16x32_bf16 v[36:39], v[36:39], v[16:19], 0
	v_mfma_f32_16x16x32_bf16 v[40:43], v[40:43], v[20:23], v[36:39]
	s_setprio 0
	s_nop 5
	v_add_u32_e32 v36, s18, v52
	v_add_u32_e32 v37, 64, v53
	v_cmp_gt_u32_e32 vcc, s97, v37
	v_cmp_gt_u32_e64 s[38:39], s19, v36
	v_fmac_f32_e32 v54, 0x3e000000, v40
	s_and_b64 vcc, vcc, s[38:39]
	v_add_u32_e32 v36, v55, v112
	v_add_u32_e32 v37, 0x41, v53
	v_cndmask_b32_e32 v40, v233, v54, vcc
	v_cmp_gt_u32_e32 vcc, s97, v37
	v_cmp_gt_u32_e64 s[38:39], s19, v36
	v_fmac_f32_e32 v44, 0x3e000000, v41
	s_and_b64 vcc, vcc, s[38:39]
	v_add_u32_e32 v36, v45, v112
	v_add_u32_e32 v37, 0x42, v53
	v_cndmask_b32_e32 v41, v233, v44, vcc
	v_cmp_gt_u32_e32 vcc, s97, v37
	v_cmp_gt_u32_e64 s[38:39], s19, v36
	v_fmac_f32_e32 v46, 0x3e000000, v42
	s_and_b64 vcc, vcc, s[38:39]
	v_add_u32_e32 v36, v47, v112
	v_add_u32_e32 v37, 0x43, v53
	v_cndmask_b32_e32 v42, v233, v46, vcc
	v_cmp_gt_u32_e32 vcc, s97, v37
	v_cmp_gt_u32_e64 s[38:39], s19, v36
	v_fmac_f32_e32 v60, 0x3e000000, v43
	s_and_b64 vcc, vcc, s[38:39]
	v_cndmask_b32_e32 v43, v233, v60, vcc
	s_setprio 1
	v_mfma_f32_16x16x32_bf16 v[24:27], v[24:27], v[16:19], 0
	v_mfma_f32_16x16x32_bf16 v[28:31], v[28:31], v[20:23], v[24:27]
	s_setprio 0
	s_nop 5
	v_add_u32_e32 v24, v61, v112
	v_add_u32_e32 v25, 0x50, v53
	v_cmp_gt_u32_e32 vcc, s97, v25
	v_cmp_gt_u32_e64 s[38:39], s19, v24
	v_fmac_f32_e32 v62, 0x3e000000, v28
	s_and_b64 vcc, vcc, s[38:39]
	v_add_u32_e32 v24, v63, v112
	v_add_u32_e32 v25, 0x51, v53
	v_cndmask_b32_e32 v28, v233, v62, vcc
	v_cmp_gt_u32_e32 vcc, s97, v25
	v_cmp_gt_u32_e64 s[38:39], s19, v24
	v_fmac_f32_e32 v56, 0x3e000000, v29
	s_and_b64 vcc, vcc, s[38:39]
	v_add_u32_e32 v24, v57, v112
	v_add_u32_e32 v25, 0x52, v53
	v_cndmask_b32_e32 v29, v233, v56, vcc
	v_cmp_gt_u32_e32 vcc, s97, v25
	v_cmp_gt_u32_e64 s[38:39], s19, v24
	v_fmac_f32_e32 v58, 0x3e000000, v30
	s_and_b64 vcc, vcc, s[38:39]
	v_add_u32_e32 v24, v59, v112
	v_add_u32_e32 v25, 0x53, v53
	v_cndmask_b32_e32 v30, v233, v58, vcc
	v_cmp_gt_u32_e32 vcc, s97, v25
	v_cmp_gt_u32_e64 s[38:39], s19, v24
	v_max_f32_e32 v24, v40, v41
	v_fmac_f32_e32 v113, 0x3e000000, v31
	s_and_b64 vcc, vcc, s[38:39]
	v_max3_f32 v24, v24, v42, v43
	v_cndmask_b32_e32 v31, v233, v113, vcc
	v_max3_f32 v24, v24, v28, v29
	v_max3_f32 v24, v24, v30, v31
	v_add_f32_e32 v25, 0x41000000, v109
	v_cmp_gt_f32_e32 vcc, v24, v25
	s_cmp_lg_u64 vcc, 0
	s_cselect_b64 s[12:13], -1, 0
	s_cbranch_vccz .Latt2_631
	v_and_b32_e32 v26, 64, v234
	v_xor_b32_e32 v25, 16, v234
	v_add_u32_e32 v26, 64, v26
	v_cmp_lt_i32_e32 vcc, v25, v26
	s_nop 1
	v_cndmask_b32_e32 v25, v234, v25, vcc
	v_lshlrev_b32_e32 v25, 2, v25
	ds_bpermute_b32 v25, v25, v24
	v_max_f32_e32 v24, v24, v24
	s_waitcnt lgkmcnt(0)
	v_max_f32_e32 v25, v25, v25
	v_max_f32_e32 v24, v24, v25
	v_xor_b32_e32 v25, 32, v234
	v_cmp_lt_i32_e32 vcc, v25, v26
	s_nop 1
	v_cndmask_b32_e32 v25, v234, v25, vcc
	v_lshlrev_b32_e32 v25, 2, v25
	ds_bpermute_b32 v25, v25, v24
	s_waitcnt lgkmcnt(0)
	v_max3_f32 v25, v109, v24, v25
	v_sub_f32_e32 v24, v109, v25
	v_mul_f32_e32 v24, 0x3fb8aa3b, v24
	v_exp_f32_e32 v24, v24
	v_mov_b32_e32 v109, v25
	s_branch .Latt2_632
.Latt2_631:
	v_mov_b32_e32 v24, 1.0
.Latt2_632:
	v_sub_f32_e32 v28, v28, v109
	v_mul_f32_e32 v28, 0x3fb8aa3b, v28
	v_sub_f32_e32 v26, v41, v109
	v_exp_f32_e32 v41, v28
	v_sub_f32_e32 v28, v29, v109
	v_mul_f32_e32 v28, 0x3fb8aa3b, v28
	v_sub_f32_e32 v27, v42, v109
	v_exp_f32_e32 v42, v28
	v_sub_f32_e32 v28, v30, v109
	v_mul_f32_e32 v28, 0x3fb8aa3b, v28
	v_sub_f32_e32 v25, v40, v109
	v_sub_f32_e32 v40, v43, v109
	v_exp_f32_e32 v43, v28
	v_sub_f32_e32 v28, v31, v109
	v_mul_f32_e32 v25, 0x3fb8aa3b, v25
	v_mul_f32_e32 v26, 0x3fb8aa3b, v26
	v_mul_f32_e32 v27, 0x3fb8aa3b, v27
	v_mul_f32_e32 v40, 0x3fb8aa3b, v40
	v_mul_f32_e32 v28, 0x3fb8aa3b, v28
	v_exp_f32_e32 v25, v25
	v_exp_f32_e32 v26, v26
	v_exp_f32_e32 v27, v27
	v_exp_f32_e32 v40, v40
	v_exp_f32_e32 v36, v28
	s_andn2_b64 vcc, exec, s[12:13]
	v_cvt_pk_bf16_f32 v28, v25, v26
	v_cvt_pk_bf16_f32 v29, v27, v40
	v_cvt_pk_bf16_f32 v30, v41, v42
	v_cvt_pk_bf16_f32 v31, v43, v36
	s_cbranch_vccnz .Latt2_634
	v_pk_mul_f32 v[2:3], v[2:3], v[24:25] op_sel_hi:[1,0]
	v_pk_mul_f32 v[0:1], v[0:1], v[24:25] op_sel_hi:[1,0]
	v_pk_mul_f32 v[6:7], v[6:7], v[24:25] op_sel_hi:[1,0]
	v_pk_mul_f32 v[4:5], v[4:5], v[24:25] op_sel_hi:[1,0]
	v_pk_mul_f32 v[10:11], v[10:11], v[24:25] op_sel_hi:[1,0]
	v_pk_mul_f32 v[8:9], v[8:9], v[24:25] op_sel_hi:[1,0]
	v_pk_mul_f32 v[32:33], v[12:13], v[24:25] op_sel_hi:[1,0]
	v_pk_mul_f32 v[34:35], v[14:15], v[24:25] op_sel_hi:[1,0]
.Latt2_634:
	v_add_f32_e32 v12, 0, v25
	v_add_f32_e32 v12, v26, v12
	v_add_f32_e32 v12, v27, v12
	v_add_f32_e32 v12, v40, v12
	v_add_f32_e32 v12, v41, v12
	v_add_f32_e32 v12, v42, v12
	v_add_f32_e32 v12, v43, v12
	v_add_f32_e32 v112, v36, v12
	ds_read_b64_tr_b16 v[114:115], v106 offset:16384
	ds_read_b64_tr_b16 v[116:117], v107 offset:16384
	ds_read_b64_tr_b16 v[118:119], v106 offset:16416
	ds_read_b64_tr_b16 v[120:121], v107 offset:16416
	ds_read_b64_tr_b16 v[122:123], v106 offset:16448
	ds_read_b64_tr_b16 v[124:125], v107 offset:16448
	ds_read_b64_tr_b16 v[126:127], v106 offset:16480
	ds_read_b64_tr_b16 v[128:129], v107 offset:16480
	v_fmac_f32_e32 v112, v111, v24
	s_setprio 1
	s_waitcnt lgkmcnt(6)
	v_mfma_f32_16x16x32_bf16 v[8:11], v[114:117], v[28:31], v[8:11]
	s_waitcnt lgkmcnt(4)
	v_mfma_f32_16x16x32_bf16 v[4:7], v[118:121], v[28:31], v[4:7]
	s_waitcnt lgkmcnt(2)
	v_mfma_f32_16x16x32_bf16 v[0:3], v[122:125], v[28:31], v[0:3]
	s_waitcnt lgkmcnt(0)
	v_mfma_f32_16x16x32_bf16 v[12:15], v[126:129], v[28:31], v[32:35]
	s_setprio 0
	s_add_i32 s16, s16, 1
	s_cmp_eq_u32 s16, 11
	s_cbranch_scc1 .Latt2_exit
	v_mov_b32_e32 v111, v112
	s_mov_b32 s18, s17
	v_mov_b32_e32 v32, v12
	v_mov_b32_e32 v33, v13
	v_mov_b32_e32 v34, v14
	v_mov_b32_e32 v35, v15
	s_branch .LBB0_621
.Latt2_exit:
	s_waitcnt vmcnt(0)
	v_mov_b64_e32 v[30:31], v[66:67]
	v_mov_b64_e32 v[26:27], v[70:71]
	v_mov_b64_e32 v[42:43], v[74:75]
	v_mov_b64_e32 v[38:39], v[78:79]
	v_mov_b64_e32 v[62:63], v[90:91]
	v_mov_b64_e32 v[58:59], v[94:95]
	v_mov_b64_e32 v[54:55], v[82:83]
	v_mov_b64_e32 v[46:47], v[86:87]
	v_mov_b64_e32 v[28:29], v[64:65]
	v_mov_b64_e32 v[24:25], v[68:69]
	v_mov_b64_e32 v[40:41], v[72:73]
	v_mov_b64_e32 v[36:37], v[76:77]
	v_mov_b64_e32 v[60:61], v[88:89]
	v_mov_b64_e32 v[56:57], v[92:93]
	v_mov_b64_e32 v[52:53], v[80:81]
	v_mov_b64_e32 v[44:45], v[84:85]
